# nt (streaming) cache hint on the 32 GU-epilogue activation stores, to reduce L2 pollution of the A/B tile stream
# speedup vs baseline: 1.0178x; 1.0045x over previous
; #define LAS __attribute__((address_space(3)))
; #define ROW_RS(u, ai, m) row_rs_lds((ai) * 128 + wr * 64 + (m) * 16 + fr, fq)
; #define ROWLOOP for (int ai = 0; ai < 2; ++ai) _Pragma("unroll") for (int m = 0; m < 4; ++m)
; __device__ __forceinline__ float row_rs_lds(int rt, int fq) {
;     extern __shared__ __attribute__((aligned(16))) unsigned char lds_raw_[];
;     const f32x4 v = *(const LAS f32x4*)((LAS unsigned char*)lds_raw_ + RS_OFF + rt * 64 + fq * 16);
;     float s = (v[0] + v[1]) + (v[2] + v[3]);
;     s = red4_sum(s);
;     return __builtin_amdgcn_rsqf(s * (1.0f / D) + EPS);
; }
;     __device__ __forceinline__ void operator()(const Acc& acc, const Unit& u, int wr, int wc, int fr, int fq) const {
;         const int col0 = u.pn * 128 + wc * 32 + fq * 8;
; #pragma unroll
;         ROWLOOP {
;             const int row = ROW_OF(u, ai, m); const float rs = ROW_RS(u, ai, m); const float c1 = -rs * LOG2E, rs2 = rs * rs;
;             f32x4 o[2];
; #pragma unroll
;             for (int n = 0; n < 2; ++n) {
;                 const f32x4 gv = acc[ai][0][m][n], gu = gv * acc[ai][1][m][n], t = gv * c1; f32x4 r;
; #pragma unroll
;                 for (int e = 0; e < 4; ++e) r[e] = __builtin_amdgcn_rcpf(1.0f + __builtin_amdgcn_exp2f(t[e]));
;                 o[n] = gu * (r * rs2);
;             }
;             *(u32x4*)(act + (size_t)row * FF + col0) = pack8(o[0], o[1]);
;         }
.LBB0_266:
.LBB0_268:
	ds_read_b128 v[188:191], v154
	ds_read_b128 v[192:195], v154 offset:1024
	ds_read_b128 v[196:199], v154 offset:2048
	ds_read_b128 v[200:203], v154 offset:3072
	ds_read_b128 v[204:207], v154 offset:8192
	ds_read_b128 v[208:211], v154 offset:9216
	ds_read_b128 v[212:215], v154 offset:10240
	ds_read_b128 v[216:219], v154 offset:11264
	v_pk_mul_f32 v[112:113], v[112:113], v[116:117]
	v_pk_mul_f32 v[114:115], v[114:115], v[118:119]
	v_pk_mul_f32 v[104:105], v[104:105], v[108:109]
	v_pk_mul_f32 v[106:107], v[106:107], v[110:111]
	s_waitcnt lgkmcnt(7)
	v_add_f32_e32 v146, v188, v189
	v_add_f32_e32 v147, v190, v191
	v_add_f32_e32 v146, v146, v147
	v_mov_b32_e32 v147, v146
	s_nop 1
	v_permlane16_swap_b32_e32 v146, v147
	v_add_f32_e32 v146, v146, v147
	v_mov_b32_e32 v147, v146
	s_nop 1
	v_permlane32_swap_b32_e32 v146, v147
	v_add_f32_e32 v146, v146, v147
	v_fmamk_f32 v146, v146, 0x3a800000, v155
	v_rsq_f32_e32 v147, v146
	v_lshl_or_b32 v148, s54, 7, v152
	v_lshl_add_u32 v146, s24, 8, v150
	v_pk_mul_f32 v[96:97], v[96:97], v[100:101]
	v_mul_f32_e32 v156, 0xbfb8aa3b, v147
	v_pk_mul_f32 v[160:161], v[120:121], v[156:157] op_sel_hi:[1,0]
	v_mul_f32_e32 v158, v147, v147
	v_exp_f32_e32 v147, v160
	v_exp_f32_e32 v149, v161
	v_pk_mul_f32 v[160:161], v[122:123], v[156:157] op_sel_hi:[1,0]
	v_pk_mul_f32 v[120:121], v[124:125], v[120:121]
	v_add_f32_e32 v147, 1.0, v147
	v_exp_f32_e32 v157, v160
	v_rcp_f32_e32 v160, v147
	v_exp_f32_e32 v147, v161
	v_add_f32_e32 v149, 1.0, v149
	v_rcp_f32_e32 v161, v149
	v_add_f32_e32 v149, 1.0, v157
	v_add_f32_e32 v147, 1.0, v147
	v_rcp_f32_e32 v162, v149
	v_rcp_f32_e32 v163, v147
	v_pk_mul_f32 v[122:123], v[126:127], v[122:123]
	v_pk_mul_f32 v[124:125], v[158:159], v[160:161] op_sel_hi:[0,1]
	v_pk_mul_f32 v[120:121], v[120:121], v[124:125]
	v_pk_mul_f32 v[126:127], v[158:159], v[162:163] op_sel_hi:[0,1]
	v_pk_mul_f32 v[122:123], v[122:123], v[126:127]
	v_pk_mul_f32 v[126:127], v[116:117], v[156:157] op_sel_hi:[1,0]
	v_pk_mul_f32 v[124:125], v[118:119], v[156:157] op_sel_hi:[1,0]
	v_exp_f32_e32 v126, v126
	v_exp_f32_e32 v127, v127
	v_exp_f32_e32 v124, v124
	v_exp_f32_e32 v125, v125
	v_add_f32_e32 v126, 1.0, v126
	v_add_f32_e32 v127, 1.0, v127
	v_add_f32_e32 v124, 1.0, v124
	v_add_f32_e32 v125, 1.0, v125
	v_rcp_f32_e32 v126, v126
	v_rcp_f32_e32 v127, v127
	v_rcp_f32_e32 v124, v124
	v_rcp_f32_e32 v125, v125
	v_ashrrev_i32_e32 v149, 31, v148
	v_pk_mul_f32 v[116:117], v[158:159], v[126:127] op_sel_hi:[0,1]
	v_pk_mul_f32 v[112:113], v[112:113], v[116:117]
	v_pk_mul_f32 v[118:119], v[158:159], v[124:125] op_sel_hi:[0,1]
	v_pk_mul_f32 v[114:115], v[114:115], v[118:119]
	v_cvt_pk_bf16_f32 v116, v120, v121
	v_cvt_pk_bf16_f32 v117, v122, v123
	v_cvt_pk_bf16_f32 v118, v112, v113
	v_mov_b64_e32 v[112:113], s[10:11]
	v_cvt_pk_bf16_f32 v119, v114, v115
	v_mad_i64_i32 v[124:125], s[24:25], v146, s53, v[112:113]
	v_pk_mul_f32 v[98:99], v[98:99], v[102:103]
	v_pk_mul_f32 v[88:89], v[88:89], v[92:93]
	s_waitcnt lgkmcnt(6)
	v_add_f32_e32 v114, v192, v193
	v_add_f32_e32 v115, v194, v195
	v_add_f32_e32 v114, v114, v115
	v_mov_b32_e32 v115, v114
	s_nop 1
	v_permlane16_swap_b32_e32 v114, v115
	v_add_f32_e32 v114, v114, v115
	v_mov_b32_e32 v115, v114
	s_nop 1
	v_permlane32_swap_b32_e32 v114, v115
	v_add_f32_e32 v114, v114, v115
	v_fmamk_f32 v114, v114, 0x3a800000, v155
	v_rsq_f32_e32 v122, v114
	v_lshlrev_b64 v[114:115], 1, v[148:149]
	v_lshl_add_u64 v[120:121], v[124:125], 0, v[114:115]
	global_store_dwordx4 v[120:121], v[116:119], off nt
	s_and_b64 vcc, exec, s[6:7]
	s_cbranch_vccz .Lalb_1
	s_barrier
.Lalb_1:
	v_pk_mul_f32 v[90:91], v[90:91], v[94:95]
	v_pk_mul_f32 v[80:81], v[80:81], v[84:85]
	v_mul_f32_e32 v116, 0xbfb8aa3b, v122
	v_pk_mul_f32 v[118:119], v[108:109], v[116:117] op_sel_hi:[1,0]
	v_pk_mul_f32 v[82:83], v[82:83], v[86:87]
	v_exp_f32_e32 v117, v118
	v_mul_f32_e32 v118, v122, v122
	v_exp_f32_e32 v119, v119
	v_pk_mul_f32 v[72:73], v[72:73], v[76:77]
	v_pk_mul_f32 v[120:121], v[110:111], v[116:117] op_sel_hi:[1,0]
	v_add_f32_e32 v117, 1.0, v117
	v_rcp_f32_e32 v122, v117
	v_exp_f32_e32 v117, v120
	v_exp_f32_e32 v121, v121
	v_add_f32_e32 v119, 1.0, v119
	v_rcp_f32_e32 v123, v119
	v_add_f32_e32 v117, 1.0, v117
	v_rcp_f32_e32 v120, v117
	v_add_f32_e32 v117, 1.0, v121
	v_rcp_f32_e32 v121, v117
	v_pk_mul_f32 v[108:109], v[118:119], v[122:123] op_sel_hi:[0,1]
	v_pk_mul_f32 v[104:105], v[104:105], v[108:109]
	v_pk_mul_f32 v[108:109], v[102:103], v[116:117] op_sel_hi:[1,0]
	v_pk_mul_f32 v[110:111], v[118:119], v[120:121] op_sel_hi:[0,1]
	v_pk_mul_f32 v[106:107], v[106:107], v[110:111]
	v_pk_mul_f32 v[110:111], v[100:101], v[116:117] op_sel_hi:[1,0]
	v_exp_f32_e32 v108, v108
	v_exp_f32_e32 v110, v110
	v_exp_f32_e32 v111, v111
	v_exp_f32_e32 v109, v109
	v_add_f32_e32 v108, 1.0, v108
	v_add_f32_e32 v110, 1.0, v110
	v_add_f32_e32 v111, 1.0, v111
	v_add_f32_e32 v109, 1.0, v109
	v_rcp_f32_e32 v110, v110
	v_rcp_f32_e32 v111, v111
	v_rcp_f32_e32 v108, v108
	v_rcp_f32_e32 v109, v109
	v_pk_mul_f32 v[74:75], v[74:75], v[78:79]
	v_pk_mul_f32 v[100:101], v[118:119], v[110:111] op_sel_hi:[0,1]
	v_pk_mul_f32 v[64:65], v[64:65], v[68:69]
	v_pk_mul_f32 v[102:103], v[118:119], v[108:109] op_sel_hi:[0,1]
	v_pk_mul_f32 v[102:103], v[98:99], v[102:103]
	v_pk_mul_f32 v[98:99], v[96:97], v[100:101]
	v_cvt_pk_bf16_f32 v96, v104, v105
	v_cvt_pk_bf16_f32 v97, v106, v107
	v_or_b32_e32 v104, 16, v146
	v_cvt_pk_bf16_f32 v98, v98, v99
	v_cvt_pk_bf16_f32 v99, v102, v103
	v_pk_mul_f32 v[66:67], v[66:67], v[70:71]
	v_pk_mul_f32 v[56:57], v[56:57], v[60:61]
	v_pk_mul_f32 v[58:59], v[58:59], v[62:63]
	v_pk_mul_f32 v[48:49], v[48:49], v[52:53]
	s_waitcnt lgkmcnt(5)
; #define LAS __attribute__((address_space(3)))
; #define ROW_RS(u, ai, m) row_rs_lds((ai) * 128 + wr * 64 + (m) * 16 + fr, fq)
; #define ROWLOOP for (int ai = 0; ai < 2; ++ai) _Pragma("unroll") for (int m = 0; m < 4; ++m)
; __device__ __forceinline__ float row_rs_lds(int rt, int fq) {
;     extern __shared__ __attribute__((aligned(16))) unsigned char lds_raw_[];
;     const f32x4 v = *(const LAS f32x4*)((LAS unsigned char*)lds_raw_ + RS_OFF + rt * 64 + fq * 16);
;     float s = (v[0] + v[1]) + (v[2] + v[3]);
;     s = red4_sum(s);
;     return __builtin_amdgcn_rsqf(s * (1.0f / D) + EPS);
; }
;     __device__ __forceinline__ void operator()(const Acc& acc, const Unit& u, int wr, int wc, int fr, int fq) const {
;         const int col0 = u.pn * 128 + wc * 32 + fq * 8;
; #pragma unroll
;         ROWLOOP {
;             const int row = ROW_OF(u, ai, m); const float rs = ROW_RS(u, ai, m); const float c1 = -rs * LOG2E, rs2 = rs * rs;
;             f32x4 o[2];
; #pragma unroll
;             for (int n = 0; n < 2; ++n) {
;                 const f32x4 gv = acc[ai][0][m][n], gu = gv * acc[ai][1][m][n], t = gv * c1; f32x4 r;
; #pragma unroll
;                 for (int e = 0; e < 4; ++e) r[e] = __builtin_amdgcn_rcpf(1.0f + __builtin_amdgcn_exp2f(t[e]));
;                 o[n] = gu * (r * rs2);
;             }
;             *(u32x4*)(act + (size_t)row * FF + col0) = pack8(o[0], o[1]);
;         }
	v_add_f32_e32 v100, v196, v197
	v_add_f32_e32 v101, v198, v199
	v_add_f32_e32 v100, v100, v101
	v_mov_b32_e32 v101, v100
	s_nop 1
	v_permlane16_swap_b32_e32 v100, v101
	v_add_f32_e32 v100, v100, v101
	v_mov_b32_e32 v101, v100
	s_nop 1
	v_permlane32_swap_b32_e32 v100, v101
	v_add_f32_e32 v100, v100, v101
	v_fmamk_f32 v100, v100, 0x3a800000, v155
	v_rsq_f32_e32 v102, v100
	v_mad_i64_i32 v[100:101], s[24:25], v104, s53, v[112:113]
	v_lshl_add_u64 v[100:101], v[100:101], 0, v[114:115]
	global_store_dwordx4 v[100:101], v[96:99], off nt
	v_pk_mul_f32 v[50:51], v[50:51], v[54:55]
	v_pk_mul_f32 v[40:41], v[40:41], v[44:45]
	v_mul_f32_e32 v96, 0xbfb8aa3b, v102
	v_pk_mul_f32 v[98:99], v[92:93], v[96:97] op_sel_hi:[1,0]
	v_pk_mul_f32 v[42:43], v[42:43], v[46:47]
	v_exp_f32_e32 v97, v98
	v_mul_f32_e32 v98, v102, v102
	v_exp_f32_e32 v99, v99
	v_pk_mul_f32 v[32:33], v[32:33], v[36:37]
	v_pk_mul_f32 v[100:101], v[94:95], v[96:97] op_sel_hi:[1,0]
	v_add_f32_e32 v97, 1.0, v97
	v_rcp_f32_e32 v102, v97
	v_exp_f32_e32 v97, v100
	v_exp_f32_e32 v101, v101
	v_add_f32_e32 v99, 1.0, v99
	v_rcp_f32_e32 v103, v99
	v_add_f32_e32 v97, 1.0, v97
	v_rcp_f32_e32 v100, v97
	v_add_f32_e32 v97, 1.0, v101
	v_rcp_f32_e32 v101, v97
	v_pk_mul_f32 v[92:93], v[98:99], v[102:103] op_sel_hi:[0,1]
	v_pk_mul_f32 v[88:89], v[88:89], v[92:93]
	v_pk_mul_f32 v[92:93], v[86:87], v[96:97] op_sel_hi:[1,0]
	v_pk_mul_f32 v[94:95], v[98:99], v[100:101] op_sel_hi:[0,1]
	v_pk_mul_f32 v[90:91], v[90:91], v[94:95]
	v_pk_mul_f32 v[94:95], v[84:85], v[96:97] op_sel_hi:[1,0]
	v_exp_f32_e32 v92, v92
	v_exp_f32_e32 v94, v94
	v_exp_f32_e32 v95, v95
	v_exp_f32_e32 v93, v93
	v_add_f32_e32 v92, 1.0, v92
	v_add_f32_e32 v94, 1.0, v94
	v_add_f32_e32 v95, 1.0, v95
	v_add_f32_e32 v93, 1.0, v93
	v_rcp_f32_e32 v94, v94
	v_rcp_f32_e32 v95, v95
	v_rcp_f32_e32 v92, v92
	v_rcp_f32_e32 v93, v93
	v_pk_mul_f32 v[34:35], v[34:35], v[38:39]
	v_pk_mul_f32 v[84:85], v[98:99], v[94:95] op_sel_hi:[0,1]
	v_pk_mul_f32 v[24:25], v[24:25], v[28:29]
	v_pk_mul_f32 v[86:87], v[98:99], v[92:93] op_sel_hi:[0,1]
	v_pk_mul_f32 v[86:87], v[82:83], v[86:87]
	v_pk_mul_f32 v[82:83], v[80:81], v[84:85]
	v_cvt_pk_bf16_f32 v80, v88, v89
	v_cvt_pk_bf16_f32 v81, v90, v91
	v_or_b32_e32 v88, 32, v146
	v_cvt_pk_bf16_f32 v82, v82, v83
	v_cvt_pk_bf16_f32 v83, v86, v87
	v_pk_mul_f32 v[26:27], v[26:27], v[30:31]
	v_pk_mul_f32 v[16:17], v[16:17], v[20:21]
	v_pk_mul_f32 v[18:19], v[18:19], v[22:23]
	v_pk_mul_f32 v[8:9], v[8:9], v[12:13]
	s_waitcnt lgkmcnt(4)
	v_add_f32_e32 v84, v200, v201
	v_add_f32_e32 v85, v202, v203
	v_add_f32_e32 v84, v84, v85
	v_mov_b32_e32 v85, v84
	s_nop 1
	v_permlane16_swap_b32_e32 v84, v85
	v_add_f32_e32 v84, v84, v85
	v_mov_b32_e32 v85, v84
	s_nop 1
	v_permlane32_swap_b32_e32 v84, v85
	v_add_f32_e32 v84, v84, v85
	v_fmamk_f32 v84, v84, 0x3a800000, v155
	v_rsq_f32_e32 v86, v84
	v_mad_i64_i32 v[84:85], s[24:25], v88, s53, v[112:113]
	v_lshl_add_u64 v[84:85], v[84:85], 0, v[114:115]
	global_store_dwordx4 v[84:85], v[80:83], off nt
	v_pk_mul_f32 v[10:11], v[10:11], v[14:15]
	v_pk_mul_f32 v[0:1], v[0:1], v[4:5]
	v_mul_f32_e32 v80, 0xbfb8aa3b, v86
	v_pk_mul_f32 v[82:83], v[76:77], v[80:81] op_sel_hi:[1,0]
	v_pk_mul_f32 v[2:3], v[2:3], v[6:7]
	v_exp_f32_e32 v81, v82
	v_mul_f32_e32 v82, v86, v86
	v_exp_f32_e32 v83, v83
	s_andn2_b64 vcc, exec, s[4:5]
	v_pk_mul_f32 v[84:85], v[78:79], v[80:81] op_sel_hi:[1,0]
	v_add_f32_e32 v81, 1.0, v81
	v_rcp_f32_e32 v86, v81
	v_exp_f32_e32 v81, v84
	v_exp_f32_e32 v85, v85
	v_add_f32_e32 v83, 1.0, v83
	v_rcp_f32_e32 v87, v83
	v_add_f32_e32 v81, 1.0, v81
	v_rcp_f32_e32 v84, v81
	v_add_f32_e32 v81, 1.0, v85
	v_rcp_f32_e32 v85, v81
	v_pk_mul_f32 v[76:77], v[82:83], v[86:87] op_sel_hi:[0,1]
	v_pk_mul_f32 v[72:73], v[72:73], v[76:77]
	v_pk_mul_f32 v[76:77], v[70:71], v[80:81] op_sel_hi:[1,0]
	v_pk_mul_f32 v[78:79], v[82:83], v[84:85] op_sel_hi:[0,1]
	v_pk_mul_f32 v[74:75], v[74:75], v[78:79]
	v_pk_mul_f32 v[78:79], v[68:69], v[80:81] op_sel_hi:[1,0]
	v_exp_f32_e32 v76, v76
	v_exp_f32_e32 v78, v78
	v_exp_f32_e32 v79, v79
	v_exp_f32_e32 v77, v77
	v_add_f32_e32 v76, 1.0, v76
	v_add_f32_e32 v78, 1.0, v78
	v_add_f32_e32 v79, 1.0, v79
	v_add_f32_e32 v77, 1.0, v77
	v_rcp_f32_e32 v78, v78
	v_rcp_f32_e32 v79, v79
	v_rcp_f32_e32 v76, v76
	v_rcp_f32_e32 v77, v77
	s_mov_b64 s[4:5], -1
	v_pk_mul_f32 v[68:69], v[82:83], v[78:79] op_sel_hi:[0,1]
	v_pk_mul_f32 v[70:71], v[82:83], v[76:77] op_sel_hi:[0,1]
	v_pk_mul_f32 v[70:71], v[66:67], v[70:71]
	v_pk_mul_f32 v[66:67], v[64:65], v[68:69]
	v_cvt_pk_bf16_f32 v64, v72, v73
	v_cvt_pk_bf16_f32 v65, v74, v75
	v_or_b32_e32 v72, 48, v146
	v_cvt_pk_bf16_f32 v66, v66, v67
	v_cvt_pk_bf16_f32 v67, v70, v71
	s_waitcnt lgkmcnt(3)
; #define LAS __attribute__((address_space(3)))
; #define ROW_RS(u, ai, m) row_rs_lds((ai) * 128 + wr * 64 + (m) * 16 + fr, fq)
; #define ROWLOOP for (int ai = 0; ai < 2; ++ai) _Pragma("unroll") for (int m = 0; m < 4; ++m)
; __device__ __forceinline__ float row_rs_lds(int rt, int fq) {
;     extern __shared__ __attribute__((aligned(16))) unsigned char lds_raw_[];
;     const f32x4 v = *(const LAS f32x4*)((LAS unsigned char*)lds_raw_ + RS_OFF + rt * 64 + fq * 16);
;     float s = (v[0] + v[1]) + (v[2] + v[3]);
;     s = red4_sum(s);
;     return __builtin_amdgcn_rsqf(s * (1.0f / D) + EPS);
; }
;     __device__ __forceinline__ void operator()(const Acc& acc, const Unit& u, int wr, int wc, int fr, int fq) const {
;         const int col0 = u.pn * 128 + wc * 32 + fq * 8;
; #pragma unroll
;         ROWLOOP {
;             const int row = ROW_OF(u, ai, m); const float rs = ROW_RS(u, ai, m); const float c1 = -rs * LOG2E, rs2 = rs * rs;
;             f32x4 o[2];
; #pragma unroll
;             for (int n = 0; n < 2; ++n) {
;                 const f32x4 gv = acc[ai][0][m][n], gu = gv * acc[ai][1][m][n], t = gv * c1; f32x4 r;
; #pragma unroll
;                 for (int e = 0; e < 4; ++e) r[e] = __builtin_amdgcn_rcpf(1.0f + __builtin_amdgcn_exp2f(t[e]));
;                 o[n] = gu * (r * rs2);
;             }
;             *(u32x4*)(act + (size_t)row * FF + col0) = pack8(o[0], o[1]);
;         }
	v_add_f32_e32 v68, v204, v205
	v_add_f32_e32 v69, v206, v207
	v_add_f32_e32 v68, v68, v69
	v_mov_b32_e32 v69, v68
	s_nop 1
	v_permlane16_swap_b32_e32 v68, v69
	v_add_f32_e32 v68, v68, v69
	v_mov_b32_e32 v69, v68
	s_nop 1
	v_permlane32_swap_b32_e32 v68, v69
	v_add_f32_e32 v68, v68, v69
	v_fmamk_f32 v68, v68, 0x3a800000, v155
	v_rsq_f32_e32 v70, v68
	v_mad_i64_i32 v[68:69], s[24:25], v72, s53, v[112:113]
	v_lshl_add_u64 v[68:69], v[68:69], 0, v[114:115]
	global_store_dwordx4 v[68:69], v[64:67], off nt
	s_nop 1
	v_mul_f32_e32 v64, 0xbfb8aa3b, v70
	v_pk_mul_f32 v[66:67], v[60:61], v[64:65] op_sel_hi:[1,0]
	s_nop 0
	v_exp_f32_e32 v65, v66
	v_mul_f32_e32 v66, v70, v70
	v_exp_f32_e32 v67, v67
	v_pk_mul_f32 v[68:69], v[62:63], v[64:65] op_sel_hi:[1,0]
	v_add_f32_e32 v65, 1.0, v65
	v_rcp_f32_e32 v70, v65
	v_exp_f32_e32 v65, v68
	v_exp_f32_e32 v69, v69
	v_add_f32_e32 v67, 1.0, v67
	v_rcp_f32_e32 v71, v67
	v_add_f32_e32 v65, 1.0, v65
	v_rcp_f32_e32 v68, v65
	v_add_f32_e32 v65, 1.0, v69
	v_rcp_f32_e32 v69, v65
	v_pk_mul_f32 v[60:61], v[66:67], v[70:71] op_sel_hi:[0,1]
	v_pk_mul_f32 v[56:57], v[56:57], v[60:61]
	v_pk_mul_f32 v[60:61], v[54:55], v[64:65] op_sel_hi:[1,0]
	v_pk_mul_f32 v[62:63], v[66:67], v[68:69] op_sel_hi:[0,1]
	v_pk_mul_f32 v[58:59], v[58:59], v[62:63]
	v_pk_mul_f32 v[62:63], v[52:53], v[64:65] op_sel_hi:[1,0]
	v_exp_f32_e32 v60, v60
	v_exp_f32_e32 v62, v62
	v_exp_f32_e32 v63, v63
	v_exp_f32_e32 v61, v61
	v_add_f32_e32 v60, 1.0, v60
	v_add_f32_e32 v62, 1.0, v62
	v_add_f32_e32 v63, 1.0, v63
	v_add_f32_e32 v61, 1.0, v61
	v_rcp_f32_e32 v62, v62
	v_rcp_f32_e32 v63, v63
	v_rcp_f32_e32 v60, v60
	v_rcp_f32_e32 v61, v61
	v_pk_mul_f32 v[52:53], v[66:67], v[62:63] op_sel_hi:[0,1]
	v_pk_mul_f32 v[54:55], v[66:67], v[60:61] op_sel_hi:[0,1]
	v_pk_mul_f32 v[54:55], v[50:51], v[54:55]
	v_pk_mul_f32 v[50:51], v[48:49], v[52:53]
	v_cvt_pk_bf16_f32 v48, v56, v57
	v_cvt_pk_bf16_f32 v49, v58, v59
	v_add_u32_e32 v56, 0x80, v146
	v_cvt_pk_bf16_f32 v50, v50, v51
	v_cvt_pk_bf16_f32 v51, v54, v55
	s_waitcnt lgkmcnt(2)
	v_add_f32_e32 v52, v208, v209
	v_add_f32_e32 v53, v210, v211
	v_add_f32_e32 v52, v52, v53
	v_mov_b32_e32 v53, v52
	s_nop 1
	v_permlane16_swap_b32_e32 v52, v53
	v_add_f32_e32 v52, v52, v53
	v_mov_b32_e32 v53, v52
	s_nop 1
	v_permlane32_swap_b32_e32 v52, v53
	v_add_f32_e32 v52, v52, v53
	v_fmamk_f32 v52, v52, 0x3a800000, v155
	v_rsq_f32_e32 v54, v52
	v_mad_i64_i32 v[52:53], s[24:25], v56, s53, v[112:113]
	v_lshl_add_u64 v[52:53], v[52:53], 0, v[114:115]
	global_store_dwordx4 v[52:53], v[48:51], off nt
	s_nop 1
	v_mul_f32_e32 v48, 0xbfb8aa3b, v54
	v_pk_mul_f32 v[50:51], v[44:45], v[48:49] op_sel_hi:[1,0]
	s_nop 0
	v_exp_f32_e32 v49, v50
	v_mul_f32_e32 v50, v54, v54
	v_exp_f32_e32 v51, v51
	v_pk_mul_f32 v[52:53], v[46:47], v[48:49] op_sel_hi:[1,0]
	v_add_f32_e32 v49, 1.0, v49
	v_rcp_f32_e32 v54, v49
	v_exp_f32_e32 v49, v52
	v_exp_f32_e32 v53, v53
	v_add_f32_e32 v51, 1.0, v51
	v_rcp_f32_e32 v55, v51
	v_add_f32_e32 v49, 1.0, v49
	v_rcp_f32_e32 v52, v49
	v_add_f32_e32 v49, 1.0, v53
	v_rcp_f32_e32 v53, v49
	v_pk_mul_f32 v[44:45], v[50:51], v[54:55] op_sel_hi:[0,1]
	v_pk_mul_f32 v[40:41], v[40:41], v[44:45]
	v_pk_mul_f32 v[44:45], v[38:39], v[48:49] op_sel_hi:[1,0]
	v_pk_mul_f32 v[46:47], v[50:51], v[52:53] op_sel_hi:[0,1]
	v_pk_mul_f32 v[42:43], v[42:43], v[46:47]
	v_pk_mul_f32 v[46:47], v[36:37], v[48:49] op_sel_hi:[1,0]
	v_exp_f32_e32 v44, v44
	v_exp_f32_e32 v46, v46
	v_exp_f32_e32 v47, v47
	v_exp_f32_e32 v45, v45
	v_add_f32_e32 v44, 1.0, v44
	v_add_f32_e32 v46, 1.0, v46
	v_add_f32_e32 v47, 1.0, v47
	v_add_f32_e32 v45, 1.0, v45
	v_rcp_f32_e32 v46, v46
	v_rcp_f32_e32 v47, v47
	v_rcp_f32_e32 v44, v44
	v_rcp_f32_e32 v45, v45
	v_pk_mul_f32 v[36:37], v[50:51], v[46:47] op_sel_hi:[0,1]
	v_pk_mul_f32 v[38:39], v[50:51], v[44:45] op_sel_hi:[0,1]
	v_pk_mul_f32 v[38:39], v[34:35], v[38:39]
	v_pk_mul_f32 v[34:35], v[32:33], v[36:37]
	v_cvt_pk_bf16_f32 v32, v40, v41
	v_cvt_pk_bf16_f32 v33, v42, v43
	v_add_u32_e32 v40, 0x90, v146
	v_cvt_pk_bf16_f32 v34, v34, v35
	v_cvt_pk_bf16_f32 v35, v38, v39
	s_waitcnt lgkmcnt(1)
; #define LAS __attribute__((address_space(3)))
; #define PG8_BAR __builtin_amdgcn_s_barrier()
; #define ROW_RS(u, ai, m) row_rs_lds((ai) * 128 + wr * 64 + (m) * 16 + fr, fq)
; #define ROWLOOP for (int ai = 0; ai < 2; ++ai) _Pragma("unroll") for (int m = 0; m < 4; ++m)
; template <class Epi>
; __device__ __forceinline__ void gemm_phase(LAS unsigned char* lds, const int tid, const Gemm g, const StaticOrder& S, const Epi& E) {
;     ...
;         if (!has_next) break;
; #pragma unroll
;         for (int a = 0; a < 2; ++a)
; #pragma unroll
;             for (int b = 0; b < 2; ++b)
; #pragma unroll
;                 for (int m = 0; m < 4; ++m)
; #pragma unroll
;                     for (int n = 0; n < 2; ++n) acc[a][b][m][n] = (f32x4){0.f, 0.f, 0.f, 0.f};
;         cur = nxt; cA = nA; cB = nB; ++ui;
;         if (wr == 1) PG8_BAR;
;     }
; __device__ __forceinline__ float row_rs_lds(int rt, int fq) {
;     extern __shared__ __attribute__((aligned(16))) unsigned char lds_raw_[];
;     const f32x4 v = *(const LAS f32x4*)((LAS unsigned char*)lds_raw_ + RS_OFF + rt * 64 + fq * 16);
;     float s = (v[0] + v[1]) + (v[2] + v[3]);
;     s = red4_sum(s);
;     return __builtin_amdgcn_rsqf(s * (1.0f / D) + EPS);
; }
;     __device__ __forceinline__ void operator()(const Acc& acc, const Unit& u, int wr, int wc, int fr, int fq) const {
;         const int col0 = u.pn * 128 + wc * 32 + fq * 8;
; #pragma unroll
;         ROWLOOP {
;             const int row = ROW_OF(u, ai, m); const float rs = ROW_RS(u, ai, m); const float c1 = -rs * LOG2E, rs2 = rs * rs;
;             f32x4 o[2];
; #pragma unroll
;             for (int n = 0; n < 2; ++n) {
;                 const f32x4 gv = acc[ai][0][m][n], gu = gv * acc[ai][1][m][n], t = gv * c1; f32x4 r;
; #pragma unroll
;                 for (int e = 0; e < 4; ++e) r[e] = __builtin_amdgcn_rcpf(1.0f + __builtin_amdgcn_exp2f(t[e]));
;                 o[n] = gu * (r * rs2);
;             }
;             *(u32x4*)(act + (size_t)row * FF + col0) = pack8(o[0], o[1]);
;         }
	v_add_f32_e32 v36, v212, v213
	v_add_f32_e32 v37, v214, v215
	v_add_f32_e32 v36, v36, v37
	v_mov_b32_e32 v37, v36
	s_nop 1
	v_permlane16_swap_b32_e32 v36, v37
	v_add_f32_e32 v36, v36, v37
	v_mov_b32_e32 v37, v36
	s_nop 1
	v_permlane32_swap_b32_e32 v36, v37
	v_add_f32_e32 v36, v36, v37
	v_fmamk_f32 v36, v36, 0x3a800000, v155
	v_rsq_f32_e32 v38, v36
	v_mad_i64_i32 v[36:37], s[24:25], v40, s53, v[112:113]
	v_lshl_add_u64 v[36:37], v[36:37], 0, v[114:115]
	global_store_dwordx4 v[36:37], v[32:35], off nt
	s_nop 1
	v_mul_f32_e32 v32, 0xbfb8aa3b, v38
	v_pk_mul_f32 v[34:35], v[28:29], v[32:33] op_sel_hi:[1,0]
	s_nop 0
	v_exp_f32_e32 v33, v34
	v_mul_f32_e32 v34, v38, v38
	v_exp_f32_e32 v35, v35
	v_pk_mul_f32 v[36:37], v[30:31], v[32:33] op_sel_hi:[1,0]
	v_add_f32_e32 v33, 1.0, v33
	v_rcp_f32_e32 v38, v33
	v_exp_f32_e32 v33, v36
	v_exp_f32_e32 v37, v37
	v_add_f32_e32 v35, 1.0, v35
	v_rcp_f32_e32 v39, v35
	v_add_f32_e32 v33, 1.0, v33
	v_rcp_f32_e32 v36, v33
	v_add_f32_e32 v33, 1.0, v37
	v_rcp_f32_e32 v37, v33
	v_pk_mul_f32 v[28:29], v[34:35], v[38:39] op_sel_hi:[0,1]
	v_pk_mul_f32 v[24:25], v[24:25], v[28:29]
	v_pk_mul_f32 v[28:29], v[22:23], v[32:33] op_sel_hi:[1,0]
	v_pk_mul_f32 v[30:31], v[34:35], v[36:37] op_sel_hi:[0,1]
	v_pk_mul_f32 v[26:27], v[26:27], v[30:31]
	v_pk_mul_f32 v[30:31], v[20:21], v[32:33] op_sel_hi:[1,0]
	v_exp_f32_e32 v28, v28
	v_exp_f32_e32 v30, v30
	v_exp_f32_e32 v31, v31
	v_exp_f32_e32 v29, v29
	v_add_f32_e32 v28, 1.0, v28
	v_add_f32_e32 v30, 1.0, v30
	v_add_f32_e32 v31, 1.0, v31
	v_add_f32_e32 v29, 1.0, v29
	v_rcp_f32_e32 v30, v30
	v_rcp_f32_e32 v31, v31
	v_rcp_f32_e32 v28, v28
	v_rcp_f32_e32 v29, v29
	v_pk_mul_f32 v[20:21], v[34:35], v[30:31] op_sel_hi:[0,1]
	v_pk_mul_f32 v[22:23], v[34:35], v[28:29] op_sel_hi:[0,1]
	v_pk_mul_f32 v[22:23], v[18:19], v[22:23]
	v_pk_mul_f32 v[18:19], v[16:17], v[20:21]
	v_cvt_pk_bf16_f32 v16, v24, v25
	v_cvt_pk_bf16_f32 v17, v26, v27
	v_add_u32_e32 v24, 0xa0, v146
	v_cvt_pk_bf16_f32 v18, v18, v19
	v_cvt_pk_bf16_f32 v19, v22, v23
	s_waitcnt lgkmcnt(0)
	v_add_f32_e32 v20, v216, v217
	v_add_f32_e32 v21, v218, v219
	v_add_f32_e32 v20, v20, v21
	v_mov_b32_e32 v21, v20
	s_nop 1
	v_permlane16_swap_b32_e32 v20, v21
	v_add_f32_e32 v20, v20, v21
	v_mov_b32_e32 v21, v20
	s_nop 1
	v_permlane32_swap_b32_e32 v20, v21
	v_add_f32_e32 v20, v20, v21
	v_fmamk_f32 v20, v20, 0x3a800000, v155
	v_rsq_f32_e32 v22, v20
	v_mad_i64_i32 v[20:21], s[24:25], v24, s53, v[112:113]
	v_lshl_add_u64 v[20:21], v[20:21], 0, v[114:115]
	global_store_dwordx4 v[20:21], v[16:19], off nt
	s_nop 1
	v_mul_f32_e32 v16, 0xbfb8aa3b, v22
	v_pk_mul_f32 v[18:19], v[12:13], v[16:17] op_sel_hi:[1,0]
	s_nop 0
	v_exp_f32_e32 v17, v18
	v_mul_f32_e32 v18, v22, v22
	v_exp_f32_e32 v19, v19
	v_pk_mul_f32 v[20:21], v[14:15], v[16:17] op_sel_hi:[1,0]
	v_add_f32_e32 v17, 1.0, v17
	v_rcp_f32_e32 v22, v17
	v_exp_f32_e32 v17, v20
	v_exp_f32_e32 v21, v21
	v_add_f32_e32 v19, 1.0, v19
	v_rcp_f32_e32 v23, v19
	v_add_f32_e32 v17, 1.0, v17
	v_rcp_f32_e32 v20, v17
	v_add_f32_e32 v17, 1.0, v21
	v_rcp_f32_e32 v21, v17
	v_pk_mul_f32 v[12:13], v[18:19], v[22:23] op_sel_hi:[0,1]
	v_pk_mul_f32 v[8:9], v[8:9], v[12:13]
	v_pk_mul_f32 v[12:13], v[6:7], v[16:17] op_sel_hi:[1,0]
	v_pk_mul_f32 v[14:15], v[18:19], v[20:21] op_sel_hi:[0,1]
	v_pk_mul_f32 v[10:11], v[10:11], v[14:15]
	v_pk_mul_f32 v[14:15], v[4:5], v[16:17] op_sel_hi:[1,0]
	v_exp_f32_e32 v12, v12
	v_exp_f32_e32 v14, v14
	v_exp_f32_e32 v15, v15
	v_exp_f32_e32 v13, v13
	v_add_f32_e32 v12, 1.0, v12
	v_add_f32_e32 v14, 1.0, v14
	v_add_f32_e32 v15, 1.0, v15
	v_add_f32_e32 v13, 1.0, v13
	v_rcp_f32_e32 v14, v14
	v_rcp_f32_e32 v15, v15
	v_rcp_f32_e32 v12, v12
	v_rcp_f32_e32 v13, v13
	v_pk_mul_f32 v[4:5], v[18:19], v[14:15] op_sel_hi:[0,1]
	v_pk_mul_f32 v[6:7], v[18:19], v[12:13] op_sel_hi:[0,1]
	v_pk_mul_f32 v[6:7], v[2:3], v[6:7]
	v_pk_mul_f32 v[2:3], v[0:1], v[4:5]
	v_add_u32_e32 v4, 0xb0, v146
	v_mad_i64_i32 v[4:5], s[24:25], v4, s53, v[112:113]
	v_lshl_add_u64 v[4:5], v[4:5], 0, v[114:115]
	v_cvt_pk_bf16_f32 v0, v8, v9
	v_cvt_pk_bf16_f32 v1, v10, v11
	v_cvt_pk_bf16_f32 v2, v2, v3
	v_cvt_pk_bf16_f32 v3, v6, v7
	global_store_dwordx4 v[4:5], v[0:3], off nt
	s_cbranch_vccnz .LBB0_258
	s_andn2_b64 vcc, exec, s[8:9]
	s_cbranch_vccnz .LBB0_257
	s_barrier
	s_branch .LBB0_257
